# queue phases: first job of each phase is static (job = bid), dynamic claims offset by grid size; removes the 512-way contended returning atomic at phase start
# baseline (speedup 1.0000x reference)
.LBB0_271:
	s_or_b64 exec, exec, s[0:1]
	v_readlane_b32 s0, v227, 19
	v_readlane_b32 s1, v227, 20
	s_xor_b64 s[0:1], s[0:1], -1
	v_writelane_b32 v227, s0, 23
	s_waitcnt lgkmcnt(0)
	s_barrier
	v_writelane_b32 v227, s1, 24
	s_barrier
	s_and_saveexec_b64 s[0:1], s[54:55]
	s_cbranch_execz .LBB0_275
	s_mov_b64 s[6:7], exec
	v_mbcnt_lo_u32_b32 v0, s6, 0
	v_mbcnt_hi_u32_b32 v0, s7, v0
	v_cmp_eq_u32_e32 vcc, 0, v0
	s_and_saveexec_b64 s[4:5], vcc
	s_cbranch_execz .LBB0_274
	s_bcnt1_i32_b64 s6, s[6:7]
	v_mov_b32_e32 v1, s6
	v_readlane_b32 s6, v231, 49
	v_readlane_b32 s7, v231, 50
	s_nop 4
	v_readlane_b32 s6, v231, 0
	s_nop 1
	v_mov_b32_e32 v1, s6

.LBB0_325:
	s_waitcnt vmcnt(63) expcnt(7) lgkmcnt(15)
	s_barrier
	s_and_saveexec_b64 s[0:1], s[54:55]
	s_cbranch_execz .LBB0_278
	s_mov_b64 s[6:7], exec
	v_mbcnt_lo_u32_b32 v0, s6, 0
	v_mbcnt_hi_u32_b32 v0, s7, v0
	v_cmp_eq_u32_e32 vcc, 0, v0
	s_and_saveexec_b64 s[4:5], vcc
	s_cbranch_execz .LBB0_277
	s_bcnt1_i32_b64 s6, s[6:7]
	v_mov_b32_e32 v1, s6
	v_readlane_b32 s6, v231, 49
	v_readlane_b32 s7, v231, 50
	s_nop 4
	global_atomic_add v1, v97, v1, s[6:7] sc0
	s_waitcnt vmcnt(0)
	v_readlane_b32 s6, v228, 24
	s_nop 1
	v_add_u32_e32 v1, s6, v1
	s_branch .LBB0_277

.LBB0_380:
	s_or_b64 exec, exec, s[0:1]
	s_waitcnt lgkmcnt(0)
	s_barrier
	s_barrier
	s_and_saveexec_b64 s[0:1], s[54:55]
	s_cbranch_execz .LBB0_384
	s_mov_b64 s[6:7], exec
	v_mbcnt_lo_u32_b32 v0, s6, 0
	v_mbcnt_hi_u32_b32 v0, s7, v0
	v_cmp_eq_u32_e32 vcc, 0, v0
	s_and_saveexec_b64 s[4:5], vcc
	s_cbranch_execz .LBB0_383
	s_bcnt1_i32_b64 s6, s[6:7]
	v_mov_b32_e32 v1, s6
	v_readlane_b32 s6, v231, 49
	v_readlane_b32 s7, v231, 50
	s_nop 4
	v_readlane_b32 s6, v231, 0
	s_nop 1
	v_mov_b32_e32 v1, s6

.LBB0_484:
	s_waitcnt vmcnt(63) expcnt(7) lgkmcnt(15)
	s_barrier
	s_and_saveexec_b64 s[0:1], s[54:55]
	s_cbranch_execz .LBB0_387
	s_mov_b64 s[6:7], exec
	v_mbcnt_lo_u32_b32 v0, s6, 0
	v_mbcnt_hi_u32_b32 v0, s7, v0
	v_cmp_eq_u32_e32 vcc, 0, v0
	s_and_saveexec_b64 s[4:5], vcc
	s_cbranch_execz .LBB0_386
	s_bcnt1_i32_b64 s6, s[6:7]
	v_mov_b32_e32 v1, s6
	v_readlane_b32 s6, v231, 49
	v_readlane_b32 s7, v231, 50
	s_nop 4
	global_atomic_add v1, v97, v1, s[6:7] offset:4 sc0
	s_waitcnt vmcnt(0)
	v_readlane_b32 s6, v228, 24
	s_nop 1
	v_add_u32_e32 v1, s6, v1
	s_branch .LBB0_386

.LBB0_624:
	s_waitcnt vmcnt(63) expcnt(7) lgkmcnt(15)
	s_barrier
	s_and_saveexec_b64 s[0:1], s[54:55]
	s_cbranch_execz .LBB0_628
	s_mov_b64 s[6:7], exec
	v_mbcnt_lo_u32_b32 v0, s6, 0
	v_mbcnt_hi_u32_b32 v0, s7, v0
	v_cmp_eq_u32_e32 vcc, 0, v0
	s_and_saveexec_b64 s[4:5], vcc
	s_cbranch_execz .LBB0_627
	s_bcnt1_i32_b64 s6, s[6:7]
	v_mov_b32_e32 v1, s6
	v_readlane_b32 s6, v231, 49
	v_readlane_b32 s7, v231, 50
	s_nop 4
	v_readlane_b32 s6, v231, 0
	s_nop 1
	v_mov_b32_e32 v1, s6

.LBB0_735:
	global_store_dword v[0:1], v2, off offset:4
	s_waitcnt vmcnt(63) expcnt(7) lgkmcnt(15)
	s_barrier
	s_and_saveexec_b64 s[0:1], s[54:55]
	s_cbranch_execz .LBB0_631
	s_mov_b64 s[6:7], exec
	v_mbcnt_lo_u32_b32 v0, s6, 0
	v_mbcnt_hi_u32_b32 v0, s7, v0
	v_cmp_eq_u32_e32 vcc, 0, v0
	s_and_saveexec_b64 s[4:5], vcc
	s_cbranch_execz .LBB0_630
	s_bcnt1_i32_b64 s6, s[6:7]
	v_mov_b32_e32 v1, s6
	v_readlane_b32 s6, v231, 49
	v_readlane_b32 s7, v231, 50
	s_nop 4
	global_atomic_add v1, v97, v1, s[6:7] offset:8 sc0
	s_waitcnt vmcnt(0)
	v_readlane_b32 s6, v228, 24
	s_nop 1
	v_add_u32_e32 v1, s6, v1
	s_branch .LBB0_630
